# grid barrier arrival path: kernarg load and the two LDS set-up reads issued together with one wait, on top of v27
# speedup vs baseline: 1.0034x; 1.0028x over previous
.LBB0_112:
	s_mov_b64 s[4:5], s[38:39]
	s_waitcnt vmcnt(0)
	s_barrier
	s_and_saveexec_b64 s[0:1], s[58:59]
	s_cbranch_execz .LBB0_164
	v_readlane_b32 s6, v254, 28
	s_load_dwordx2 s[4:5], s[4:5], 0x80
	s_getreg_b32 s3, hwreg(HW_REG_XCC_ID, 0, 4)
	v_mov_b32_e32 v2, s6
	v_readlane_b32 s6, v254, 29
	s_and_b32 s3, s3, 15
	s_waitcnt vmcnt(0) expcnt(0)
	ds_read_b32 v3, v2
	v_mov_b32_e32 v0, s6
	ds_read_b32 v2, v0
	s_waitcnt lgkmcnt(0)
	v_cmp_ne_u32_e32 vcc, 0, v3
	s_cbranch_vccnz .LBB0_128
	s_add_u32 s6, s4, 0x4200
	s_addc_u32 s7, s5, 0
	s_add_u32 s10, s4, 0x4400
	s_addc_u32 s11, s5, 0
	s_add_u32 s12, s4, 0x4500
	s_addc_u32 s13, s5, 0
	s_add_u32 s14, s4, 0x4600
	s_addc_u32 s15, s5, 0
	s_add_u32 s16, s4, 0x4700
	s_addc_u32 s17, s5, 0
	s_add_u32 s18, s4, 0x4800
	s_addc_u32 s19, s5, 0
	s_add_u32 s40, s4, 0x4900
	s_addc_u32 s41, s5, 0
	s_add_u32 s42, s4, 0x4a00
	s_addc_u32 s43, s5, 0
	s_add_u32 s46, s4, 0x4b00
	s_addc_u32 s47, s5, 0
	s_add_u32 s48, s4, 0x4c00
	s_addc_u32 s49, s5, 0
	s_add_u32 s50, s4, 0x4d00
	s_addc_u32 s51, s5, 0
	s_add_u32 s54, s4, 0x4e00
	s_addc_u32 s55, s5, 0
	s_add_u32 s56, s4, 0x4f00
	s_addc_u32 s57, s5, 0
	s_add_u32 s64, s4, 0x5000
	s_addc_u32 s65, s5, 0
	s_add_u32 s66, s4, 0x5100
	s_addc_u32 s67, s5, 0
	s_add_u32 s70, s4, 0x5200
	s_addc_u32 s71, s5, 0
	s_add_u32 s72, s4, 0x5300
	s_addc_u32 s73, s5, 0
	s_mov_b32 s24, 1
	s_branch .LBB0_116

.LBB0_294:
	s_mov_b64 s[6:7], s[38:39]
	s_waitcnt vmcnt(0)
	s_waitcnt vmcnt(63) expcnt(7) lgkmcnt(15)
	s_barrier
	s_and_saveexec_b64 s[4:5], s[58:59]
	s_cbranch_execz .LBB0_346
	v_readlane_b32 s8, v254, 28
	s_load_dwordx2 s[6:7], s[6:7], 0x80
	s_getreg_b32 s3, hwreg(HW_REG_XCC_ID, 0, 4)
	v_mov_b32_e32 v2, s8
	v_readlane_b32 s8, v254, 29
	s_and_b32 s3, s3, 15
	s_waitcnt vmcnt(0) expcnt(0)
	ds_read_b32 v3, v2
	v_mov_b32_e32 v0, s8
	ds_read_b32 v2, v0
	s_waitcnt lgkmcnt(0)
	v_cmp_ne_u32_e32 vcc, 0, v3
	s_cbranch_vccnz .LBB0_310
	s_add_u32 s8, s6, 0x4200
	s_addc_u32 s9, s7, 0
	s_add_u32 s10, s6, 0x4400
	s_addc_u32 s11, s7, 0
	s_add_u32 s12, s6, 0x4500
	s_addc_u32 s13, s7, 0
	s_add_u32 s14, s6, 0x4600
	s_addc_u32 s15, s7, 0
	s_add_u32 s16, s6, 0x4700
	s_addc_u32 s17, s7, 0
	s_add_u32 s18, s6, 0x4800
	s_addc_u32 s19, s7, 0
	s_add_u32 s40, s6, 0x4900
	s_addc_u32 s41, s7, 0
	s_add_u32 s46, s6, 0x4a00
	s_addc_u32 s47, s7, 0
	s_add_u32 s50, s6, 0x4b00
	s_addc_u32 s51, s7, 0
	s_add_u32 s54, s6, 0x4c00
	s_addc_u32 s55, s7, 0
	s_add_u32 s56, s6, 0x4d00
	s_addc_u32 s57, s7, 0
	s_add_u32 s64, s6, 0x4e00
	s_addc_u32 s65, s7, 0
	s_add_u32 s66, s6, 0x4f00
	s_addc_u32 s67, s7, 0
	s_add_u32 s70, s6, 0x5000
	s_addc_u32 s71, s7, 0
	s_add_u32 s72, s6, 0x5100
	s_addc_u32 s73, s7, 0
	s_add_u32 s80, s6, 0x5200
	s_addc_u32 s81, s7, 0
	s_add_u32 s92, s6, 0x5300
	s_addc_u32 s93, s7, 0
	s_mov_b32 s24, 1
	s_branch .LBB0_298

.LBB0_469:
	s_mov_b64 s[4:5], s[38:39]
	s_waitcnt vmcnt(0)
	s_waitcnt vmcnt(63) expcnt(7) lgkmcnt(15)
	s_barrier
	s_and_saveexec_b64 s[0:1], s[58:59]
	s_cbranch_execz .LBB0_521
	v_readlane_b32 s6, v254, 28
	s_load_dwordx2 s[4:5], s[4:5], 0x80
	s_getreg_b32 s3, hwreg(HW_REG_XCC_ID, 0, 4)
	v_mov_b32_e32 v2, s6
	v_readlane_b32 s6, v254, 29
	s_and_b32 s3, s3, 15
	s_waitcnt vmcnt(0) expcnt(0)
	ds_read_b32 v3, v2
	v_mov_b32_e32 v0, s6
	ds_read_b32 v2, v0
	s_waitcnt lgkmcnt(0)
	v_cmp_ne_u32_e32 vcc, 0, v3
	s_cbranch_vccnz .LBB0_485
	s_add_u32 s6, s4, 0x4200
	s_addc_u32 s7, s5, 0
	s_add_u32 s8, s4, 0x4400
	s_addc_u32 s9, s5, 0
	s_add_u32 s10, s4, 0x4500
	s_addc_u32 s11, s5, 0
	s_add_u32 s12, s4, 0x4600
	s_addc_u32 s13, s5, 0
	s_add_u32 s14, s4, 0x4700
	s_addc_u32 s15, s5, 0
	s_add_u32 s16, s4, 0x4800
	s_addc_u32 s17, s5, 0
	s_add_u32 s18, s4, 0x4900
	s_addc_u32 s19, s5, 0
	s_add_u32 s40, s4, 0x4a00
	s_addc_u32 s41, s5, 0
	s_add_u32 s50, s4, 0x4b00
	s_addc_u32 s51, s5, 0
	s_add_u32 s54, s4, 0x4c00
	s_addc_u32 s55, s5, 0
	s_add_u32 s56, s4, 0x4d00
	s_addc_u32 s57, s5, 0
	s_add_u32 s64, s4, 0x4e00
	s_addc_u32 s65, s5, 0
	s_add_u32 s66, s4, 0x4f00
	s_addc_u32 s67, s5, 0
	s_add_u32 s70, s4, 0x5000
	s_addc_u32 s71, s5, 0
	s_add_u32 s72, s4, 0x5100
	s_addc_u32 s73, s5, 0
	s_add_u32 s80, s4, 0x5200
	s_addc_u32 s81, s5, 0
	s_add_u32 s92, s4, 0x5300
	s_addc_u32 s93, s5, 0
	s_mov_b32 s24, 1
	s_branch .LBB0_473

.LBB0_530:
	s_mov_b64 s[4:5], s[38:39]
	s_waitcnt vmcnt(0)
	s_barrier
	s_and_saveexec_b64 s[0:1], s[58:59]
	s_cbranch_execz .LBB0_582
	v_readlane_b32 s6, v254, 28
	s_load_dwordx2 s[4:5], s[4:5], 0x80
	s_getreg_b32 s3, hwreg(HW_REG_XCC_ID, 0, 4)
	v_mov_b32_e32 v2, s6
	v_readlane_b32 s6, v254, 29
	s_and_b32 s3, s3, 15
	s_waitcnt vmcnt(0) expcnt(0)
	ds_read_b32 v3, v2
	v_mov_b32_e32 v0, s6
	ds_read_b32 v2, v0
	s_waitcnt lgkmcnt(0)
	v_cmp_ne_u32_e32 vcc, 0, v3
	s_cbranch_vccnz .LBB0_546
	s_add_u32 s6, s4, 0x4200
	s_addc_u32 s7, s5, 0
	s_add_u32 s8, s4, 0x4400
	s_addc_u32 s9, s5, 0
	s_add_u32 s10, s4, 0x4500
	s_addc_u32 s11, s5, 0
	s_add_u32 s12, s4, 0x4600
	s_addc_u32 s13, s5, 0
	s_add_u32 s14, s4, 0x4700
	s_addc_u32 s15, s5, 0
	s_add_u32 s16, s4, 0x4800
	s_addc_u32 s17, s5, 0
	s_add_u32 s18, s4, 0x4900
	s_addc_u32 s19, s5, 0
	s_add_u32 s40, s4, 0x4a00
	s_addc_u32 s41, s5, 0
	s_add_u32 s48, s4, 0x4b00
	s_addc_u32 s49, s5, 0
	s_add_u32 s50, s4, 0x4c00
	s_addc_u32 s51, s5, 0
	s_add_u32 s54, s4, 0x4d00
	s_addc_u32 s55, s5, 0
	s_add_u32 s56, s4, 0x4e00
	s_addc_u32 s57, s5, 0
	s_add_u32 s64, s4, 0x4f00
	s_addc_u32 s65, s5, 0
	s_add_u32 s66, s4, 0x5000
	s_addc_u32 s67, s5, 0
	s_add_u32 s70, s4, 0x5100
	s_addc_u32 s71, s5, 0
	s_add_u32 s72, s4, 0x5200
	s_addc_u32 s73, s5, 0
	s_add_u32 s80, s4, 0x5300
	s_addc_u32 s81, s5, 0
	s_mov_b32 s24, 1
	s_branch .LBB0_534

.LBB0_654:
	s_mov_b64 s[4:5], s[38:39]
	s_waitcnt vmcnt(0)
	s_waitcnt lgkmcnt(0)
	s_barrier
	s_and_saveexec_b64 s[0:1], s[58:59]
	s_cbranch_execz .LBB0_166
	v_readlane_b32 s6, v254, 28
	s_load_dwordx2 s[4:5], s[4:5], 0x80
	s_getreg_b32 s3, hwreg(HW_REG_XCC_ID, 0, 4)
	v_mov_b32_e32 v2, s6
	v_readlane_b32 s6, v254, 29
	s_and_b32 s3, s3, 15
	s_waitcnt vmcnt(0) expcnt(0)
	ds_read_b32 v3, v2
	v_mov_b32_e32 v0, s6
	ds_read_b32 v2, v0
	s_waitcnt lgkmcnt(0)
	v_cmp_ne_u32_e32 vcc, 0, v3
	s_cbranch_vccnz .LBB0_670
	s_add_u32 s6, s4, 0x4200
	s_addc_u32 s7, s5, 0
	s_add_u32 s8, s4, 0x4400
	s_addc_u32 s9, s5, 0
	s_add_u32 s12, s4, 0x4500
	s_addc_u32 s13, s5, 0
	s_add_u32 s14, s4, 0x4600
	s_addc_u32 s15, s5, 0
	s_add_u32 s16, s4, 0x4700
	s_addc_u32 s17, s5, 0
	s_add_u32 s18, s4, 0x4800
	s_addc_u32 s19, s5, 0
	s_add_u32 s40, s4, 0x4900
	s_addc_u32 s41, s5, 0
	s_add_u32 s48, s4, 0x4a00
	s_addc_u32 s49, s5, 0
	s_add_u32 s50, s4, 0x4b00
	s_addc_u32 s51, s5, 0
	s_add_u32 s54, s4, 0x4c00
	s_addc_u32 s55, s5, 0
	s_add_u32 s56, s4, 0x4d00
	s_addc_u32 s57, s5, 0
	s_add_u32 s64, s4, 0x4e00
	s_addc_u32 s65, s5, 0
	s_add_u32 s66, s4, 0x4f00
	s_addc_u32 s67, s5, 0
	s_add_u32 s70, s4, 0x5000
	s_addc_u32 s71, s5, 0
	s_add_u32 s72, s4, 0x5100
	s_addc_u32 s73, s5, 0
	s_add_u32 s80, s4, 0x5200
	s_addc_u32 s81, s5, 0
	s_add_u32 s92, s4, 0x5300
	s_addc_u32 s93, s5, 0
	s_mov_b32 s24, 1
	s_branch .LBB0_658

.LBB0_810:
	s_mov_b64 s[4:5], s[38:39]
	s_waitcnt vmcnt(0)
	s_barrier
	s_and_saveexec_b64 s[0:1], s[58:59]
	s_cbranch_execz .LBB0_862
	v_readlane_b32 s6, v254, 28
	s_load_dwordx2 s[4:5], s[4:5], 0x80
	s_getreg_b32 s3, hwreg(HW_REG_XCC_ID, 0, 4)
	v_mov_b32_e32 v2, s6
	v_readlane_b32 s6, v254, 29
	s_and_b32 s3, s3, 15
	s_waitcnt vmcnt(0) expcnt(0)
	ds_read_b32 v3, v2
	v_mov_b32_e32 v0, s6
	ds_read_b32 v2, v0
	s_waitcnt lgkmcnt(0)
	v_cmp_ne_u32_e32 vcc, 0, v3
	s_cbranch_vccnz .LBB0_826
	s_add_u32 s6, s4, 0x4200
	s_addc_u32 s7, s5, 0
	s_add_u32 s8, s4, 0x4400
	s_addc_u32 s9, s5, 0
	s_add_u32 s12, s4, 0x4500
	s_addc_u32 s13, s5, 0
	s_add_u32 s14, s4, 0x4600
	s_addc_u32 s15, s5, 0
	s_add_u32 s16, s4, 0x4700
	s_addc_u32 s17, s5, 0
	s_add_u32 s18, s4, 0x4800
	s_addc_u32 s19, s5, 0
	s_add_u32 s40, s4, 0x4900
	s_addc_u32 s41, s5, 0
	s_add_u32 s42, s4, 0x4a00
	s_addc_u32 s43, s5, 0
	s_add_u32 s46, s4, 0x4b00
	s_addc_u32 s47, s5, 0
	s_add_u32 s48, s4, 0x4c00
	s_addc_u32 s49, s5, 0
	s_add_u32 s50, s4, 0x4d00
	s_addc_u32 s51, s5, 0
	s_add_u32 s54, s4, 0x4e00
	s_addc_u32 s55, s5, 0
	s_add_u32 s56, s4, 0x4f00
	s_addc_u32 s57, s5, 0
	s_add_u32 s64, s4, 0x5000
	s_addc_u32 s65, s5, 0
	s_add_u32 s66, s4, 0x5100
	s_addc_u32 s67, s5, 0
	s_add_u32 s70, s4, 0x5200
	s_addc_u32 s71, s5, 0
	s_add_u32 s72, s4, 0x5300
	s_addc_u32 s73, s5, 0
	s_mov_b32 s24, 1
	s_branch .LBB0_814

.LBB0_1023:
	s_andn2_b64 vcc, exec, s[16:17]
	s_cbranch_vccnz .LBB0_27
	s_mov_b64 s[4:5], s[38:39]
	s_waitcnt vmcnt(0)
	s_barrier
	s_and_saveexec_b64 s[0:1], s[58:59]
	s_cbranch_execz .LBB0_26
	v_readlane_b32 s6, v254, 28
	s_load_dwordx2 s[4:5], s[4:5], 0x80
	s_getreg_b32 s3, hwreg(HW_REG_XCC_ID, 0, 4)
	v_mov_b32_e32 v2, s6
	v_readlane_b32 s6, v254, 29
	s_and_b32 s3, s3, 15
	s_waitcnt vmcnt(0) expcnt(0)
	ds_read_b32 v3, v2
	v_mov_b32_e32 v0, s6
	ds_read_b32 v2, v0
	s_waitcnt lgkmcnt(0)
	v_cmp_ne_u32_e32 vcc, 0, v3
	s_cbranch_vccnz .LBB0_1040
	s_add_u32 s6, s4, 0x4200
	s_addc_u32 s7, s5, 0
	s_add_u32 s8, s4, 0x4400
	s_addc_u32 s9, s5, 0
	s_add_u32 s10, s4, 0x4500
	s_addc_u32 s11, s5, 0
	s_add_u32 s12, s4, 0x4600
	s_addc_u32 s13, s5, 0
	s_add_u32 s14, s4, 0x4700
	s_addc_u32 s15, s5, 0
	s_add_u32 s16, s4, 0x4800
	s_addc_u32 s17, s5, 0
	s_add_u32 s18, s4, 0x4900
	s_addc_u32 s19, s5, 0
	s_add_u32 s40, s4, 0x4a00
	s_addc_u32 s41, s5, 0
	s_add_u32 s42, s4, 0x4b00
	s_addc_u32 s43, s5, 0
	s_add_u32 s46, s4, 0x4c00
	s_addc_u32 s47, s5, 0
	s_add_u32 s48, s4, 0x4d00
	s_addc_u32 s49, s5, 0
	s_add_u32 s50, s4, 0x4e00
	s_addc_u32 s51, s5, 0
	s_add_u32 s54, s4, 0x4f00
	s_addc_u32 s55, s5, 0
	s_add_u32 s56, s4, 0x5000
	s_addc_u32 s57, s5, 0
	s_add_u32 s64, s4, 0x5100
	s_addc_u32 s65, s5, 0
	s_add_u32 s66, s4, 0x5200
	s_addc_u32 s67, s5, 0
	s_add_u32 s70, s4, 0x5300
	s_addc_u32 s71, s5, 0
	s_mov_b32 s24, 1
	s_branch .LBB0_1028
